# v044 + MLA unit prologue: vmcnt(0) before the rope-q LDS park relaxed to vmcnt(10) so the first two K/V tile DMAs stay in flight
# baseline (speedup 1.0000x reference)
.LBB0_1575:
	s_lshl_b32 s2, s47, 4
	s_ashr_i32 s20, s47, 8
	s_and_b32 s2, s2, 0xffffff00
	s_add_i32 s16, s2, 0x2000
	s_lshl_b32 s2, s20, 12
	s_and_b32 s6, s47, 15
	s_ashr_i32 s21, s20, 31
	s_ashr_i32 s3, s2, 31
	s_add_u32 s2, s2, 0x2400
	s_addc_u32 s3, s3, 0
	s_ashr_i32 s17, s16, 31
	s_mul_i32 s19, s16, 0x1800
	s_mul_hi_i32 s18, s16, 0x1800
	s_add_u32 s19, s28, s19
	s_addc_u32 s18, s29, s18
	s_mul_i32 s22, s6, 0x180
	s_add_u32 s22, s19, s22
	s_addc_u32 s23, s18, 0
	s_lshl_b64 s[18:19], s[20:21], 20
	s_lshl_b64 s[24:25], s[20:21], 21
	s_add_u32 s26, s30, s24
	s_addc_u32 s27, s31, s25
	s_lshl_b32 s50, s6, 7
	s_lshl_b32 s6, s6, 8
	s_add_u32 s26, s26, s6
	s_addc_u32 s27, s27, 0
	s_add_u32 s24, s34, s24
	v_lshlrev_b32_e32 v130, 1, v140
	v_add_u32_e32 v20, 0xc000, v167
	s_addc_u32 s25, s35, s25
	v_lshl_add_u64 v[2:3], s[22:23], 0, v[130:131]
	v_mov_b32_e32 v139, v131
	v_readfirstlane_b32 s22, v20
	v_add_u32_e32 v22, 0xe000, v167
	s_add_u32 s24, s24, s6
	v_lshl_add_u64 v[14:15], v[2:3], 0, v[138:139]
	v_lshl_add_u64 v[18:19], s[26:27], 0, v[132:133]
	s_mov_b32 m0, s22
	v_readfirstlane_b32 s22, v22
	s_addc_u32 s25, s25, 0
	s_lshl_b64 s[20:21], s[20:21], 16
	global_load_dwordx4 v[98:101], v[14:15], off
	global_load_dwordx4 v[102:105], v[14:15], off offset:32
	global_load_dwordx4 v[106:109], v[14:15], off offset:64
	global_load_dwordx4 v[110:113], v[14:15], off offset:96
	global_load_dwordx4 v[114:117], v[14:15], off offset:128
	global_load_dwordx4 v[118:121], v[14:15], off offset:160
	global_load_dwordx4 v[122:125], v[14:15], off offset:192
	global_load_dwordx4 v[126:129], v[14:15], off offset:224
	global_load_dwordx4 v[2:5], v[14:15], off offset:256
	global_load_dwordx4 v[6:9], v[14:15], off offset:288
	global_load_dwordx4 v[10:13], v[14:15], off offset:320
	s_nop 0
	global_load_dwordx4 v[14:17], v[14:15], off offset:352
	v_lshl_add_u64 v[20:21], v[18:19], 0, s[8:9]
	global_load_lds_dwordx4 v[18:19], off
	s_mov_b32 m0, s22
	v_readfirstlane_b32 s22, v167
	v_add_u32_e32 v24, 0x2000, v167
	s_add_u32 s54, s36, s20
	global_load_lds_dwordx4 v[20:21], off
	v_lshl_add_u64 v[20:21], s[24:25], 0, v[134:135]
	s_mov_b32 m0, s22
	v_readfirstlane_b32 s22, v24
	s_addc_u32 s55, s37, s21
	global_load_lds_dwordx4 v[20:21], off
	v_lshl_add_u64 v[22:23], v[20:21], 0, s[8:9]
	s_mov_b32 m0, s22
	v_readfirstlane_b32 s22, v168
	v_add_u32_e32 v179, s42, v182
	global_load_lds_dwordx4 v[22:23], off
	v_lshl_add_u64 v[22:23], s[54:55], 0, v[136:137]
	s_mov_b32 m0, s22
	v_readfirstlane_b32 s22, v179
	global_load_lds_dwordx4 v[22:23], off
	v_lshl_add_u64 v[24:25], v[18:19], 0, s[10:11]
	s_mov_b32 m0, s22
	v_add_u32_e32 v180, s43, v182
	global_load_lds_dwordx4 v[24:25], off
	v_readfirstlane_b32 s22, v180
	v_add_u32_e32 v24, 0x4000, v167
	v_lshl_add_u64 v[18:19], v[18:19], 0, s[12:13]
	s_mov_b32 m0, s22
	v_readfirstlane_b32 s22, v24
	global_load_lds_dwordx4 v[18:19], off
	v_lshl_add_u64 v[18:19], v[20:21], 0, s[10:11]
	s_mov_b32 m0, s22
	v_add_u32_e32 v181, s44, v182
	global_load_lds_dwordx4 v[18:19], off
	v_lshl_add_u64 v[18:19], v[20:21], 0, s[12:13]
	v_add_u32_e32 v20, 0x6000, v167
	s_lshl_b64 s[24:25], s[2:3], 7
	v_readfirstlane_b32 s22, v20
	s_mov_b32 m0, s22
	v_readfirstlane_b32 s22, v181
	global_load_lds_dwordx4 v[18:19], off
	v_lshl_add_u64 v[18:19], v[22:23], 0, s[14:15]
	s_mov_b32 m0, s22
	s_lshl_b64 s[22:23], s[2:3], 11
	global_load_lds_dwordx4 v[18:19], off
	s_add_u32 s51, s34, s6
	s_waitcnt vmcnt(10)
	ds_write_b128 v175, v[2:5]
	ds_write_b128 v176, v[6:9]
	ds_write_b128 v177, v[10:13]
	ds_write_b128 v178, v[14:17]
	s_addc_u32 s54, s35, 0
	v_mov_b32_e32 v16, v131
	v_mov_b32_e32 v17, v131
	s_add_u32 s55, s30, s6
	v_mov_b32_e32 v2, v131
	v_mov_b32_e32 v3, v131
	v_mov_b32_e32 v4, v131
	v_mov_b32_e32 v5, v131
	v_mov_b32_e32 v6, v131
	v_mov_b32_e32 v7, v131
	v_mov_b32_e32 v8, v131
	v_mov_b32_e32 v9, v131
	v_mov_b32_e32 v10, v131
	v_mov_b32_e32 v11, v131
	v_mov_b32_e32 v12, v131
	v_mov_b32_e32 v13, v131
	v_mov_b32_e32 v14, v131
	v_mov_b32_e32 v15, v131
	v_mov_b64_e32 v[64:65], v[16:17]
	v_mov_b64_e32 v[48:49], v[16:17]
	v_mov_b64_e32 v[32:33], v[16:17]
	s_addc_u32 s56, s31, 0
	v_mov_b64_e32 v[62:63], v[14:15]
	v_mov_b64_e32 v[60:61], v[12:13]
	v_mov_b64_e32 v[58:59], v[10:11]
	v_mov_b64_e32 v[56:57], v[8:9]
	v_mov_b64_e32 v[54:55], v[6:7]
	v_mov_b64_e32 v[52:53], v[4:5]
	v_mov_b64_e32 v[50:51], v[2:3]
	v_mov_b64_e32 v[46:47], v[14:15]
	v_mov_b64_e32 v[44:45], v[12:13]
	v_mov_b64_e32 v[42:43], v[10:11]
	v_mov_b64_e32 v[40:41], v[8:9]
	v_mov_b64_e32 v[38:39], v[6:7]
	v_mov_b64_e32 v[36:37], v[4:5]
	v_mov_b64_e32 v[34:35], v[2:3]
	v_mov_b64_e32 v[30:31], v[14:15]
	v_mov_b64_e32 v[28:29], v[12:13]
	v_mov_b64_e32 v[26:27], v[10:11]
	v_mov_b64_e32 v[24:25], v[8:9]
	v_mov_b64_e32 v[22:23], v[6:7]
	v_mov_b64_e32 v[20:21], v[4:5]
	v_mov_b64_e32 v[18:19], v[2:3]
	s_mov_b32 s57, s7
	s_mov_b32 s58, s7
	v_mov_b32_e32 v139, 0xf149f2ca
	v_mov_b32_e32 v184, 0
	s_cmpk_gt_u32 s58, 0x46
	s_mov_b64 s[2:3], -1
	s_cbranch_scc0 .LBB0_1578
	s_branch .LBB0_1577

.LBB0_1591:
	s_and_b32 s22, s26, 0xffffff00
	s_ashr_i32 s23, s22, 31
	s_lshl_b64 s[2:3], s[22:23], 7
	s_lshl_b64 s[24:25], s[22:23], 12
	s_and_b32 s22, s44, 15
	s_lshl_b32 s22, s22, 8
	s_or_b32 s24, s24, s22
	s_lshl_b32 s22, s45, 4
	s_and_b32 s22, s22, 0xffffff00
	s_and_b32 s47, s45, 15
	s_ashr_i32 s23, s22, 31
	s_add_u32 s50, s22, 0x400
	s_addc_u32 s51, s23, 0
	s_mul_i32 s54, s22, 0x1800
	s_mul_hi_i32 s46, s22, 0x1800
	s_add_u32 s54, s28, s54
	s_addc_u32 s46, s29, s46
	s_mul_i32 s55, s47, 0x180
	s_add_u32 s54, s54, s55
	s_addc_u32 s55, s46, 0
	s_lshl_b64 s[56:57], s[50:51], 12
	s_add_u32 s58, s30, s56
	s_addc_u32 s59, s31, s57
	s_lshl_b32 s46, s47, 7
	s_lshl_b32 s47, s47, 8
	s_add_u32 s58, s58, s47
	s_addc_u32 s59, s59, 0
	s_add_u32 s56, s34, s56
	s_addc_u32 s57, s35, s57
	v_add_u32_e32 v20, 0xc000, v167
	s_add_u32 s56, s56, s47
	v_lshl_add_u64 v[2:3], s[54:55], 0, v[130:131]
	v_mov_b32_e32 v139, v131
	v_readfirstlane_b32 s47, v20
	v_add_u32_e32 v22, 0xe000, v167
	v_lshl_add_u64 v[14:15], v[2:3], 0, v[138:139]
	v_lshl_add_u64 v[18:19], s[58:59], 0, v[132:133]
	s_mov_b32 m0, s47
	v_readfirstlane_b32 s47, v22
	s_addc_u32 s57, s57, 0
	s_lshl_b64 s[50:51], s[50:51], 7
	global_load_dwordx4 v[98:101], v[14:15], off
	global_load_dwordx4 v[102:105], v[14:15], off offset:32
	global_load_dwordx4 v[106:109], v[14:15], off offset:64
	global_load_dwordx4 v[110:113], v[14:15], off offset:96
	global_load_dwordx4 v[114:117], v[14:15], off offset:128
	global_load_dwordx4 v[118:121], v[14:15], off offset:160
	global_load_dwordx4 v[122:125], v[14:15], off offset:192
	global_load_dwordx4 v[126:129], v[14:15], off offset:224
	global_load_dwordx4 v[2:5], v[14:15], off offset:256
	global_load_dwordx4 v[6:9], v[14:15], off offset:288
	global_load_dwordx4 v[10:13], v[14:15], off offset:320
	s_nop 0
	global_load_dwordx4 v[14:17], v[14:15], off offset:352
	v_lshl_add_u64 v[20:21], v[18:19], 0, s[6:7]
	global_load_lds_dwordx4 v[18:19], off
	s_mov_b32 m0, s47
	v_readfirstlane_b32 s47, v167
	v_add_u32_e32 v24, 0x2000, v167
	s_add_u32 s50, s36, s50
	global_load_lds_dwordx4 v[20:21], off
	v_lshl_add_u64 v[20:21], s[56:57], 0, v[134:135]
	s_mov_b32 m0, s47
	v_readfirstlane_b32 s47, v24
	s_addc_u32 s51, s37, s51
	global_load_lds_dwordx4 v[20:21], off
	v_lshl_add_u64 v[22:23], v[20:21], 0, s[6:7]
	s_mov_b32 m0, s47
	v_readfirstlane_b32 s47, v168
	global_load_lds_dwordx4 v[22:23], off
	v_lshl_add_u64 v[22:23], s[50:51], 0, v[136:137]
	s_mov_b32 m0, s47
	v_readfirstlane_b32 s47, v179
	global_load_lds_dwordx4 v[22:23], off
	v_lshl_add_u64 v[24:25], v[18:19], 0, s[8:9]
	s_mov_b32 m0, s47
	v_readfirstlane_b32 s47, v180
	global_load_lds_dwordx4 v[24:25], off
	v_add_u32_e32 v24, 0x4000, v167
	v_lshl_add_u64 v[18:19], v[18:19], 0, s[10:11]
	s_mov_b32 m0, s47
	v_readfirstlane_b32 s47, v24
	global_load_lds_dwordx4 v[18:19], off
	v_lshl_add_u64 v[18:19], v[20:21], 0, s[8:9]
	s_mov_b32 m0, s47
	v_lshl_add_u64 v[146:147], v[140:141], 0, s[2:3]
	global_load_lds_dwordx4 v[18:19], off
	v_lshl_add_u64 v[18:19], v[20:21], 0, s[10:11]
	v_add_u32_e32 v20, 0x6000, v167
	v_lshl_add_u64 v[148:149], s[24:25], 0, v[142:143]
	v_readfirstlane_b32 s47, v20
	s_mov_b32 m0, s47
	v_readfirstlane_b32 s47, v181
	global_load_lds_dwordx4 v[18:19], off
	v_lshl_add_u64 v[18:19], v[22:23], 0, s[12:13]
	s_mov_b32 m0, s47
	v_lshl_add_u64 v[150:151], s[24:25], 0, v[144:145]
	global_load_lds_dwordx4 v[18:19], off
	s_waitcnt vmcnt(10)
	ds_write_b128 v175, v[2:5]
	ds_write_b128 v176, v[6:9]
	ds_write_b128 v177, v[10:13]
	ds_write_b128 v178, v[14:17]
	v_mov_b32_e32 v16, v131
	v_mov_b32_e32 v17, v131
	v_mov_b32_e32 v2, v131
	v_mov_b32_e32 v3, v131
	v_mov_b32_e32 v4, v131
	v_mov_b32_e32 v5, v131
	v_mov_b32_e32 v6, v131
	v_mov_b32_e32 v7, v131
	v_mov_b32_e32 v8, v131
	v_mov_b32_e32 v9, v131
	v_mov_b32_e32 v10, v131
	v_mov_b32_e32 v11, v131
	v_mov_b32_e32 v12, v131
	v_mov_b32_e32 v13, v131
	v_mov_b32_e32 v14, v131
	v_mov_b32_e32 v15, v131
	v_mov_b64_e32 v[64:65], v[16:17]
	v_mov_b64_e32 v[48:49], v[16:17]
	v_mov_b64_e32 v[32:33], v[16:17]
	v_mov_b64_e32 v[62:63], v[14:15]
	v_mov_b64_e32 v[60:61], v[12:13]
	v_mov_b64_e32 v[58:59], v[10:11]
	v_mov_b64_e32 v[56:57], v[8:9]
	v_mov_b64_e32 v[54:55], v[6:7]
	v_mov_b64_e32 v[52:53], v[4:5]
	v_mov_b64_e32 v[50:51], v[2:3]
	v_mov_b64_e32 v[46:47], v[14:15]
	v_mov_b64_e32 v[44:45], v[12:13]
	v_mov_b64_e32 v[42:43], v[10:11]
	v_mov_b64_e32 v[40:41], v[8:9]
	v_mov_b64_e32 v[38:39], v[6:7]
	v_mov_b64_e32 v[36:37], v[4:5]
	v_mov_b64_e32 v[34:35], v[2:3]
	v_mov_b64_e32 v[30:31], v[14:15]
	v_mov_b64_e32 v[28:29], v[12:13]
	v_mov_b64_e32 v[26:27], v[10:11]
	v_mov_b64_e32 v[24:25], v[8:9]
	v_mov_b64_e32 v[22:23], v[6:7]
	v_mov_b64_e32 v[20:21], v[4:5]
	v_mov_b64_e32 v[18:19], v[2:3]
	s_mov_b32 s47, 0
	s_mov_b32 s50, 0
	v_mov_b32_e32 v139, 0xf149f2ca
	v_mov_b32_e32 v183, 0
	s_cmp_gt_u32 s50, 2
	s_mov_b64 s[2:3], -1
	s_cbranch_scc0 .LBB0_1594
	s_branch .LBB0_1593
